# adds: A3 GEMM second round as half tiles (one per workgroup) + in-proj epilogue gate bias loaded once per tile
# baseline (speedup 1.0000x reference)
.LBB0_890:
	s_add_i32 s38, s38, 1
	s_mul_i32 s4, s38, s37
	s_mul_hi_u32 s5, s38, s0
	s_add_i32 s5, s5, s4
	s_mul_i32 s4, s38, s0
	v_readlane_b32 s99, v255, 41
	s_cmp_eq_u32 s38, 1
	s_cselect_b32 s99, s99, 0
	s_lshr_b32 s98, s1, s99
	s_add_u32 s16, s4, s98
	s_addc_u32 s17, s5, s28
	v_cmp_gt_i64_e64 s[4:5], s[16:17], v[164:165]
	s_and_b64 vcc, exec, s[4:5]
	s_cbranch_vccnz .LBB0_892
	s_ashr_i32 s10, s16, 31
	s_lshr_b32 s10, s10, 29
	s_add_i32 s10, s16, s10
	s_ashr_i32 s11, s10, 3
	s_and_b32 s10, s10, -8
	s_sub_i32 s10, s16, s10
	s_cmp_lt_i32 s10, 0
	s_cselect_b32 s12, 49, 48
	s_mul_i32 s10, s12, s10
	s_add_i32 s10, s10, s11
	s_ashr_i32 s11, s10, 31
	s_lshr_b32 s11, s11, 28
	s_add_i32 s11, s10, s11
	s_ashr_i32 s12, s11, 4
	s_lshl_b32 s12, s12, 2
	s_sub_i32 s13, 0x60, s12
	s_min_i32 s13, s13, 4
	s_abs_i32 s18, s13
	v_cvt_f32_u32_e32 v2, s18
	s_sub_i32 s22, 0, s18
	s_and_b32 s11, s11, -16
	s_sub_i32 s11, s10, s11
	v_rcp_iflag_f32_e32 v2, v2
	s_abs_i32 s10, s11
	s_xor_b32 s19, s11, s13
	s_ashr_i32 s19, s19, 31
	v_mul_f32_e32 v2, 0x4f7ffffe, v2
	v_cvt_u32_f32_e32 v2, v2
	s_nop 0
	v_readfirstlane_b32 s23, v2
	s_mul_i32 s22, s22, s23
	s_mul_hi_u32 s22, s23, s22
	s_add_i32 s23, s23, s22
	s_mul_hi_u32 s22, s10, s23
	s_mul_i32 s23, s22, s18
	s_sub_i32 s10, s10, s23
	s_add_i32 s39, s22, 1
	s_sub_i32 s23, s10, s18
	s_cmp_ge_u32 s10, s18
	s_cselect_b32 s22, s39, s22
	s_cselect_b32 s10, s23, s10
	s_add_i32 s23, s22, 1
	s_cmp_ge_u32 s10, s18
	s_cselect_b32 s10, s23, s22
	s_xor_b32 s10, s10, s19
	s_sub_i32 s10, s10, s19
	s_mul_i32 s13, s10, s13
	s_sub_i32 s11, s11, s13
	s_add_i32 s12, s11, s12
.LBB0_892:
	s_ashr_i32 s13, s12, 31
	v_cmp_lt_i64_e32 vcc, s[16:17], v[166:167]
	s_lshl_b64 s[16:17], s[12:13], 18
	s_add_u32 s16, s3, s16
	s_addc_u32 s17, s24, s17
	s_and_b32 s98, s10, 1
	s_lshl_b32 s98, s98, 9
	s_add_u32 s16, s16, s98
	s_addc_u32 s17, s17, 0
	v_readlane_b32 s98, v254, 0
	s_and_b32 s98, s98, s99
	s_lshl_b32 s98, s98, 17
	s_add_u32 s16, s16, s98
	s_addc_u32 s17, s17, 0
	s_and_b32 s98, s10, 1
	s_lshl_b32 s98, s98, 9
	s_and_b64 s[18:19], vcc, exec
	s_cselect_b32 s13, s17, s21
	s_cselect_b32 s39, s16, s20
	s_ashr_i32 s11, s10, 31
	s_lshl_b64 s[18:19], s[10:11], 18
	s_add_u32 s18, s25, s18
	s_addc_u32 s19, s26, s19
	s_add_u32 s18, s18, s98
	s_addc_u32 s19, s19, 0
	s_and_b64 s[22:23], vcc, exec
	s_cselect_b32 s11, s19, s9
	s_cselect_b32 s40, s18, s8
	s_add_u32 s41, s8, 0x100
	s_addc_u32 s42, s9, 0
	s_add_u32 s8, s20, 0x20080
	v_mov_b32_e32 v2, 0
	s_addc_u32 s9, s21, 0
	s_mov_b32 s43, -2
	v_mov_b32_e32 v3, v2
	v_mov_b32_e32 v4, v2
	v_mov_b32_e32 v5, v2
	v_mov_b32_e32 v6, v2
	v_mov_b32_e32 v7, v2
	v_mov_b32_e32 v8, v2
	v_mov_b32_e32 v9, v2
	v_mov_b32_e32 v14, v2
	v_mov_b32_e32 v15, v2
	v_mov_b32_e32 v16, v2
	v_mov_b32_e32 v17, v2
	v_mov_b32_e32 v22, v2
	v_mov_b32_e32 v23, v2
	v_mov_b32_e32 v24, v2
	v_mov_b32_e32 v25, v2
	v_mov_b32_e32 v30, v2
	v_mov_b32_e32 v31, v2
	v_mov_b32_e32 v32, v2
	v_mov_b32_e32 v33, v2
	v_mov_b32_e32 v38, v2
	v_mov_b32_e32 v39, v2
	v_mov_b32_e32 v40, v2
	v_mov_b32_e32 v41, v2
	v_mov_b32_e32 v46, v2
	v_mov_b32_e32 v47, v2
	v_mov_b32_e32 v48, v2
	v_mov_b32_e32 v49, v2
	v_mov_b32_e32 v54, v2
	v_mov_b32_e32 v55, v2
	v_mov_b32_e32 v56, v2
	v_mov_b32_e32 v57, v2
	v_mov_b32_e32 v10, v2
	v_mov_b32_e32 v11, v2
	v_mov_b32_e32 v12, v2
	v_mov_b32_e32 v13, v2
	v_mov_b32_e32 v18, v2
	v_mov_b32_e32 v19, v2
	v_mov_b32_e32 v20, v2
	v_mov_b32_e32 v21, v2
	v_mov_b32_e32 v26, v2
	v_mov_b32_e32 v27, v2
	v_mov_b32_e32 v28, v2
	v_mov_b32_e32 v29, v2
	v_mov_b32_e32 v34, v2
	v_mov_b32_e32 v35, v2
	v_mov_b32_e32 v36, v2
	v_mov_b32_e32 v37, v2
	v_mov_b32_e32 v42, v2
	v_mov_b32_e32 v43, v2
	v_mov_b32_e32 v44, v2
	v_mov_b32_e32 v45, v2
	v_mov_b32_e32 v50, v2
	v_mov_b32_e32 v51, v2
	v_mov_b32_e32 v52, v2
	v_mov_b32_e32 v53, v2
	v_mov_b32_e32 v58, v2
	v_mov_b32_e32 v59, v2
	v_mov_b32_e32 v60, v2
	v_mov_b32_e32 v61, v2
	v_mov_b32_e32 v62, v2
	v_mov_b32_e32 v63, v2
	v_mov_b32_e32 v64, v2
	v_mov_b32_e32 v65, v2
	v_mov_b32_e32 v66, v2
	v_mov_b32_e32 v67, v2
	v_mov_b32_e32 v68, v2
	v_mov_b32_e32 v69, v2
	v_mov_b32_e32 v70, v2
	v_mov_b32_e32 v71, v2
	v_mov_b32_e32 v72, v2
	v_mov_b32_e32 v73, v2
	v_mov_b32_e32 v78, v2
	v_mov_b32_e32 v79, v2
	v_mov_b32_e32 v80, v2
	v_mov_b32_e32 v81, v2
	v_mov_b32_e32 v86, v2
	v_mov_b32_e32 v87, v2
	v_mov_b32_e32 v88, v2
	v_mov_b32_e32 v89, v2
	v_mov_b32_e32 v94, v2
	v_mov_b32_e32 v95, v2
	v_mov_b32_e32 v96, v2
	v_mov_b32_e32 v97, v2
	v_mov_b32_e32 v102, v2
	v_mov_b32_e32 v103, v2
	v_mov_b32_e32 v104, v2
	v_mov_b32_e32 v105, v2
	v_mov_b32_e32 v110, v2
	v_mov_b32_e32 v111, v2
	v_mov_b32_e32 v112, v2
	v_mov_b32_e32 v113, v2
	v_mov_b32_e32 v118, v2
	v_mov_b32_e32 v119, v2
	v_mov_b32_e32 v120, v2
	v_mov_b32_e32 v121, v2
	v_mov_b32_e32 v74, v2
	v_mov_b32_e32 v75, v2
	v_mov_b32_e32 v76, v2
	v_mov_b32_e32 v77, v2
	v_mov_b32_e32 v82, v2
	v_mov_b32_e32 v83, v2
	v_mov_b32_e32 v84, v2
	v_mov_b32_e32 v85, v2
	v_mov_b32_e32 v90, v2
	v_mov_b32_e32 v91, v2
	v_mov_b32_e32 v92, v2
	v_mov_b32_e32 v93, v2
	v_mov_b32_e32 v98, v2
	v_mov_b32_e32 v99, v2
	v_mov_b32_e32 v100, v2
	v_mov_b32_e32 v101, v2
	v_mov_b32_e32 v106, v2
	v_mov_b32_e32 v107, v2
	v_mov_b32_e32 v108, v2
	v_mov_b32_e32 v109, v2
	v_mov_b32_e32 v114, v2
	v_mov_b32_e32 v115, v2
	v_mov_b32_e32 v116, v2
	v_mov_b32_e32 v117, v2
	v_mov_b32_e32 v122, v2
	v_mov_b32_e32 v123, v2
	v_mov_b32_e32 v124, v2
	v_mov_b32_e32 v125, v2
	v_mov_b32_e32 v126, v2
	v_mov_b32_e32 v127, v2
	v_mov_b32_e32 v128, v2
	v_mov_b32_e32 v129, v2
	v_readlane_b32 s99, v255, 41
	s_cmp_eq_u32 s38, 2
	s_cselect_b32 s99, s99, 0
.LBB0_893:
	s_add_u32 s20, s8, 0xfffe0080
	s_addc_u32 s21, s9, -1
	s_add_i32 s44, 0, 0x10000
	v_add_u32_e32 v150, s44, v136
	ds_read_b128 v[138:141], v150
	ds_read_b128 v[142:145], v150 offset:1024
	ds_read_b128 v[146:149], v150 offset:2048
	ds_read_b128 v[150:153], v150 offset:3072
	s_cmp_eq_u32 s43, 0
	s_cselect_b32 s23, s13, s21
	s_cselect_b32 s22, s39, s20
	s_cselect_b32 s21, s11, s42
	s_cselect_b32 s20, s40, s41
	v_lshl_add_u64 v[200:201], s[8:9], 0, v[134:135]
	s_add_i32 m0, s29, 0xc000
	ds_read_b128 v[154:157], v137
	ds_read_b128 v[158:161], v137 offset:1024
	ds_read_b128 v[176:179], v137 offset:2048
	ds_read_b128 v[180:183], v137 offset:3072
	ds_read_b128 v[184:187], v137 offset:4096
	ds_read_b128 v[188:191], v137 offset:5120
	ds_read_b128 v[192:195], v137 offset:6144
	ds_read_b128 v[196:199], v137 offset:7168
	global_load_lds_dwordx4 v[200:201], off
	v_lshl_add_u64 v[200:201], s[8:9], 0, v[132:133]
	s_add_i32 m0, s29, 0xe000
	s_nop 0
	global_load_lds_dwordx4 v[200:201], off
	s_waitcnt lgkmcnt(8)
	s_barrier
	s_waitcnt lgkmcnt(0)
	s_setprio 1
	s_waitcnt lgkmcnt(0)
	v_mfma_f32_16x16x32_bf16 v[126:129], v[138:141], v[154:157], v[126:129]
	v_mfma_f32_16x16x32_bf16 v[122:125], v[146:149], v[154:157], v[122:125]
	v_mfma_f32_16x16x32_bf16 v[114:117], v[138:141], v[176:179], v[114:117]
	v_mfma_f32_16x16x32_bf16 v[106:109], v[146:149], v[176:179], v[106:109]
	v_mfma_f32_16x16x32_bf16 v[98:101], v[138:141], v[184:187], v[98:101]
	v_mfma_f32_16x16x32_bf16 v[90:93], v[146:149], v[184:187], v[90:93]
	v_mfma_f32_16x16x32_bf16 v[82:85], v[138:141], v[192:195], v[82:85]
	v_mfma_f32_16x16x32_bf16 v[74:77], v[146:149], v[192:195], v[74:77]
	v_mfma_f32_16x16x32_bf16 v[126:129], v[142:145], v[158:161], v[126:129]
	v_mfma_f32_16x16x32_bf16 v[122:125], v[150:153], v[158:161], v[122:125]
	v_mfma_f32_16x16x32_bf16 v[114:117], v[142:145], v[180:183], v[114:117]
	v_mfma_f32_16x16x32_bf16 v[106:109], v[150:153], v[180:183], v[106:109]
	v_mfma_f32_16x16x32_bf16 v[98:101], v[142:145], v[188:191], v[98:101]
	v_mfma_f32_16x16x32_bf16 v[90:93], v[150:153], v[188:191], v[90:93]
	v_mfma_f32_16x16x32_bf16 v[82:85], v[142:145], v[196:199], v[82:85]
	v_mfma_f32_16x16x32_bf16 v[74:77], v[150:153], v[196:199], v[74:77]
	s_setprio 0
	s_barrier
	s_add_i32 s46, 0, 0x14000
	s_add_i32 s44, s44, s27
	v_add_u32_e32 v169, s46, v136
	v_lshl_add_u64 v[200:201], s[20:21], 0, v[0:1]
	s_mov_b32 m0, s44
	ds_read_b128 v[230:233], v169
	ds_read_b128 v[234:237], v169 offset:1024
	ds_read_b128 v[238:241], v169 offset:2048
	ds_read_b128 v[242:245], v169 offset:3072
	global_load_lds_dwordx4 v[200:201], off
	v_lshl_add_u64 v[246:247], s[20:21], 0, v[130:131]
	s_add_i32 m0, s44, 0x2000
	s_nop 0
	global_load_lds_dwordx4 v[246:247], off
	s_barrier
	s_waitcnt lgkmcnt(0)
	s_setprio 1
	s_waitcnt lgkmcnt(0)
	v_mfma_f32_16x16x32_bf16 v[118:121], v[230:233], v[154:157], v[118:121]
	v_mfma_f32_16x16x32_bf16 v[110:113], v[238:241], v[154:157], v[110:113]
	v_mfma_f32_16x16x32_bf16 v[102:105], v[230:233], v[176:179], v[102:105]
	v_mfma_f32_16x16x32_bf16 v[94:97], v[238:241], v[176:179], v[94:97]
	v_mfma_f32_16x16x32_bf16 v[86:89], v[230:233], v[184:187], v[86:89]
	v_mfma_f32_16x16x32_bf16 v[78:81], v[238:241], v[184:187], v[78:81]
	v_mfma_f32_16x16x32_bf16 v[70:73], v[230:233], v[192:195], v[70:73]
	v_mfma_f32_16x16x32_bf16 v[66:69], v[238:241], v[192:195], v[66:69]
	v_mfma_f32_16x16x32_bf16 v[118:121], v[234:237], v[158:161], v[118:121]
	v_mfma_f32_16x16x32_bf16 v[110:113], v[242:245], v[158:161], v[110:113]
	v_mfma_f32_16x16x32_bf16 v[102:105], v[234:237], v[180:183], v[102:105]
	v_mfma_f32_16x16x32_bf16 v[94:97], v[242:245], v[180:183], v[94:97]
	v_mfma_f32_16x16x32_bf16 v[86:89], v[234:237], v[188:191], v[86:89]
	v_mfma_f32_16x16x32_bf16 v[78:81], v[242:245], v[188:191], v[78:81]
	v_mfma_f32_16x16x32_bf16 v[70:73], v[234:237], v[196:199], v[70:73]
	v_mfma_f32_16x16x32_bf16 v[66:69], v[242:245], v[196:199], v[66:69]
	s_setprio 0
	s_mov_b32 m0, s29
	v_lshl_add_u64 v[248:249], s[22:23], 0, v[0:1]
	s_barrier
	ds_read_b128 v[154:157], v137 offset:16384
	ds_read_b128 v[158:161], v137 offset:17408
	ds_read_b128 v[176:179], v137 offset:18432
	ds_read_b128 v[180:183], v137 offset:19456
	ds_read_b128 v[184:187], v137 offset:20480
	ds_read_b128 v[188:191], v137 offset:21504
	ds_read_b128 v[192:195], v137 offset:22528
	ds_read_b128 v[196:199], v137 offset:23552
	global_load_lds_dwordx4 v[248:249], off
	v_lshl_add_u64 v[250:251], s[22:23], 0, v[130:131]
	s_mov_b32 m0, s30
	s_nop 0
	global_load_lds_dwordx4 v[250:251], off
	s_barrier
	s_waitcnt lgkmcnt(0)
	s_setprio 1
	s_waitcnt lgkmcnt(0)
	s_cmp_lg_u32 s99, 0
	s_cbranch_scc1 .La3_skip3
	v_mfma_f32_16x16x32_bf16 v[62:65], v[138:141], v[154:157], v[62:65]
	v_mfma_f32_16x16x32_bf16 v[58:61], v[146:149], v[154:157], v[58:61]
	v_mfma_f32_16x16x32_bf16 v[50:53], v[138:141], v[176:179], v[50:53]
	v_mfma_f32_16x16x32_bf16 v[42:45], v[146:149], v[176:179], v[42:45]
	v_mfma_f32_16x16x32_bf16 v[34:37], v[138:141], v[184:187], v[34:37]
	v_mfma_f32_16x16x32_bf16 v[26:29], v[146:149], v[184:187], v[26:29]
	v_mfma_f32_16x16x32_bf16 v[18:21], v[138:141], v[192:195], v[18:21]
	v_mfma_f32_16x16x32_bf16 v[10:13], v[146:149], v[192:195], v[10:13]
	v_mfma_f32_16x16x32_bf16 v[62:65], v[142:145], v[158:161], v[62:65]
	v_mfma_f32_16x16x32_bf16 v[58:61], v[150:153], v[158:161], v[58:61]
	v_mfma_f32_16x16x32_bf16 v[50:53], v[142:145], v[180:183], v[50:53]
	v_mfma_f32_16x16x32_bf16 v[42:45], v[150:153], v[180:183], v[42:45]
	v_mfma_f32_16x16x32_bf16 v[34:37], v[142:145], v[188:191], v[34:37]
	v_mfma_f32_16x16x32_bf16 v[26:29], v[150:153], v[188:191], v[26:29]
	v_mfma_f32_16x16x32_bf16 v[18:21], v[142:145], v[196:199], v[18:21]
	v_mfma_f32_16x16x32_bf16 v[10:13], v[150:153], v[196:199], v[10:13]
.La3_skip3:
	s_setprio 0
	s_barrier
	s_add_u32 s44, s20, 0x20000
	s_addc_u32 s45, s21, 0
	s_add_i32 s46, s46, s27
	v_lshl_add_u64 v[138:139], s[44:45], 0, v[0:1]
	s_mov_b32 m0, s46
	s_nop 0
	global_load_lds_dwordx4 v[138:139], off
	v_lshl_add_u64 v[138:139], s[44:45], 0, v[130:131]
	s_add_i32 m0, s46, 0x2000
	s_nop 0
	global_load_lds_dwordx4 v[138:139], off
	s_waitcnt vmcnt(6)
	s_barrier
	s_setprio 1
	s_cmp_lg_u32 s99, 0
	s_cbranch_scc1 .La3_skip4
	v_mfma_f32_16x16x32_bf16 v[54:57], v[230:233], v[154:157], v[54:57]
	v_mfma_f32_16x16x32_bf16 v[46:49], v[238:241], v[154:157], v[46:49]
	v_mfma_f32_16x16x32_bf16 v[38:41], v[230:233], v[176:179], v[38:41]
	v_mfma_f32_16x16x32_bf16 v[30:33], v[238:241], v[176:179], v[30:33]
	v_mfma_f32_16x16x32_bf16 v[22:25], v[230:233], v[184:187], v[22:25]
	v_mfma_f32_16x16x32_bf16 v[14:17], v[238:241], v[184:187], v[14:17]
	v_mfma_f32_16x16x32_bf16 v[6:9], v[230:233], v[192:195], v[6:9]
	v_mfma_f32_16x16x32_bf16 v[2:5], v[238:241], v[192:195], v[2:5]
	v_mfma_f32_16x16x32_bf16 v[54:57], v[234:237], v[158:161], v[54:57]
	v_mfma_f32_16x16x32_bf16 v[46:49], v[242:245], v[158:161], v[46:49]
	v_mfma_f32_16x16x32_bf16 v[38:41], v[234:237], v[180:183], v[38:41]
	v_mfma_f32_16x16x32_bf16 v[30:33], v[242:245], v[180:183], v[30:33]
	v_mfma_f32_16x16x32_bf16 v[22:25], v[234:237], v[188:191], v[22:25]
	v_mfma_f32_16x16x32_bf16 v[14:17], v[242:245], v[188:191], v[14:17]
	v_mfma_f32_16x16x32_bf16 v[6:9], v[234:237], v[196:199], v[6:9]
	v_mfma_f32_16x16x32_bf16 v[2:5], v[242:245], v[196:199], v[2:5]
.La3_skip4:
	s_setprio 0
	s_add_i32 s44, 0, 0x18000
	v_add_u32_e32 v150, s44, v136
	s_barrier
	ds_read_b128 v[138:141], v150
	ds_read_b128 v[142:145], v150 offset:1024
	ds_read_b128 v[146:149], v150 offset:2048
	ds_read_b128 v[150:153], v150 offset:3072
	s_add_u32 s22, s22, 0x20000
	s_addc_u32 s23, s23, 0
	s_mov_b32 m0, s31
	v_lshl_add_u64 v[230:231], s[22:23], 0, v[0:1]
	ds_read_b128 v[154:157], v137 offset:32768
	ds_read_b128 v[158:161], v137 offset:33792
	ds_read_b128 v[176:179], v137 offset:34816
	ds_read_b128 v[180:183], v137 offset:35840
	ds_read_b128 v[184:187], v137 offset:36864
	ds_read_b128 v[188:191], v137 offset:37888
	ds_read_b128 v[192:195], v137 offset:38912
	ds_read_b128 v[196:199], v137 offset:39936
	global_load_lds_dwordx4 v[230:231], off
	v_lshl_add_u64 v[230:231], s[22:23], 0, v[130:131]
	s_mov_b32 m0, s34
	s_nop 0
	global_load_lds_dwordx4 v[230:231], off
	s_waitcnt lgkmcnt(8)
	s_barrier
	s_waitcnt lgkmcnt(0)
	s_setprio 1
	s_waitcnt lgkmcnt(0)
	v_mfma_f32_16x16x32_bf16 v[126:129], v[138:141], v[154:157], v[126:129]
	v_mfma_f32_16x16x32_bf16 v[122:125], v[146:149], v[154:157], v[122:125]
	v_mfma_f32_16x16x32_bf16 v[114:117], v[138:141], v[176:179], v[114:117]
	v_mfma_f32_16x16x32_bf16 v[106:109], v[146:149], v[176:179], v[106:109]
	v_mfma_f32_16x16x32_bf16 v[98:101], v[138:141], v[184:187], v[98:101]
	v_mfma_f32_16x16x32_bf16 v[90:93], v[146:149], v[184:187], v[90:93]
	v_mfma_f32_16x16x32_bf16 v[82:85], v[138:141], v[192:195], v[82:85]
	v_mfma_f32_16x16x32_bf16 v[74:77], v[146:149], v[192:195], v[74:77]
	v_mfma_f32_16x16x32_bf16 v[126:129], v[142:145], v[158:161], v[126:129]
	v_mfma_f32_16x16x32_bf16 v[122:125], v[150:153], v[158:161], v[122:125]
	v_mfma_f32_16x16x32_bf16 v[114:117], v[142:145], v[180:183], v[114:117]
	v_mfma_f32_16x16x32_bf16 v[106:109], v[150:153], v[180:183], v[106:109]
	v_mfma_f32_16x16x32_bf16 v[98:101], v[142:145], v[188:191], v[98:101]
	v_mfma_f32_16x16x32_bf16 v[90:93], v[150:153], v[188:191], v[90:93]
	v_mfma_f32_16x16x32_bf16 v[82:85], v[142:145], v[196:199], v[82:85]
	v_mfma_f32_16x16x32_bf16 v[74:77], v[150:153], v[196:199], v[74:77]
	s_setprio 0
	s_barrier
	s_add_i32 s22, 0, 0x1c000
	s_add_i32 s23, s44, s27
	v_add_u32_e32 v169, s22, v136
	v_lshl_add_u64 v[200:201], v[200:201], 0, s[92:93]
	s_mov_b32 m0, s23
	ds_read_b128 v[230:233], v169
	ds_read_b128 v[234:237], v169 offset:1024
	ds_read_b128 v[238:241], v169 offset:2048
	ds_read_b128 v[242:245], v169 offset:3072
	global_load_lds_dwordx4 v[200:201], off
	v_lshl_add_u64 v[200:201], v[246:247], 0, s[92:93]
	s_add_i32 m0, s23, 0x2000
	s_nop 0
	global_load_lds_dwordx4 v[200:201], off
	s_barrier
	s_waitcnt lgkmcnt(0)
	s_setprio 1
	s_waitcnt lgkmcnt(0)
	v_mfma_f32_16x16x32_bf16 v[118:121], v[230:233], v[154:157], v[118:121]
	v_mfma_f32_16x16x32_bf16 v[110:113], v[238:241], v[154:157], v[110:113]
	v_mfma_f32_16x16x32_bf16 v[102:105], v[230:233], v[176:179], v[102:105]
	v_mfma_f32_16x16x32_bf16 v[94:97], v[238:241], v[176:179], v[94:97]
	v_mfma_f32_16x16x32_bf16 v[86:89], v[230:233], v[184:187], v[86:89]
	v_mfma_f32_16x16x32_bf16 v[78:81], v[238:241], v[184:187], v[78:81]
	v_mfma_f32_16x16x32_bf16 v[70:73], v[230:233], v[192:195], v[70:73]
	v_mfma_f32_16x16x32_bf16 v[66:69], v[238:241], v[192:195], v[66:69]
	v_mfma_f32_16x16x32_bf16 v[118:121], v[234:237], v[158:161], v[118:121]
	v_mfma_f32_16x16x32_bf16 v[110:113], v[242:245], v[158:161], v[110:113]
	v_mfma_f32_16x16x32_bf16 v[102:105], v[234:237], v[180:183], v[102:105]
	v_mfma_f32_16x16x32_bf16 v[94:97], v[242:245], v[180:183], v[94:97]
	v_mfma_f32_16x16x32_bf16 v[86:89], v[234:237], v[188:191], v[86:89]
	v_mfma_f32_16x16x32_bf16 v[78:81], v[242:245], v[188:191], v[78:81]
	v_mfma_f32_16x16x32_bf16 v[70:73], v[234:237], v[196:199], v[70:73]
	v_mfma_f32_16x16x32_bf16 v[66:69], v[242:245], v[196:199], v[66:69]
	s_setprio 0
	s_mov_b32 m0, s35
	v_lshl_add_u64 v[200:201], v[248:249], 0, s[92:93]
	s_barrier
	ds_read_b128 v[154:157], v137 offset:49152
	ds_read_b128 v[158:161], v137 offset:50176
	ds_read_b128 v[176:179], v137 offset:51200
	ds_read_b128 v[180:183], v137 offset:52224
	ds_read_b128 v[184:187], v137 offset:53248
	ds_read_b128 v[188:191], v137 offset:54272
	ds_read_b128 v[192:195], v137 offset:55296
	ds_read_b128 v[196:199], v137 offset:56320
	global_load_lds_dwordx4 v[200:201], off
	v_lshl_add_u64 v[200:201], v[250:251], 0, s[92:93]
	s_mov_b32 m0, s36
	s_nop 0
	global_load_lds_dwordx4 v[200:201], off
	s_barrier
	s_waitcnt lgkmcnt(0)
	s_setprio 1
	s_waitcnt lgkmcnt(0)
	s_cmp_lg_u32 s99, 0
	s_cbranch_scc1 .La3_skip7
	v_mfma_f32_16x16x32_bf16 v[62:65], v[138:141], v[154:157], v[62:65]
	v_mfma_f32_16x16x32_bf16 v[58:61], v[146:149], v[154:157], v[58:61]
	v_mfma_f32_16x16x32_bf16 v[50:53], v[138:141], v[176:179], v[50:53]
	v_mfma_f32_16x16x32_bf16 v[42:45], v[146:149], v[176:179], v[42:45]
	v_mfma_f32_16x16x32_bf16 v[34:37], v[138:141], v[184:187], v[34:37]
	v_mfma_f32_16x16x32_bf16 v[26:29], v[146:149], v[184:187], v[26:29]
	v_mfma_f32_16x16x32_bf16 v[18:21], v[138:141], v[192:195], v[18:21]
	v_mfma_f32_16x16x32_bf16 v[10:13], v[146:149], v[192:195], v[10:13]
	v_mfma_f32_16x16x32_bf16 v[62:65], v[142:145], v[158:161], v[62:65]
	v_mfma_f32_16x16x32_bf16 v[58:61], v[150:153], v[158:161], v[58:61]
	v_mfma_f32_16x16x32_bf16 v[50:53], v[142:145], v[180:183], v[50:53]
	v_mfma_f32_16x16x32_bf16 v[42:45], v[150:153], v[180:183], v[42:45]
	v_mfma_f32_16x16x32_bf16 v[34:37], v[142:145], v[188:191], v[34:37]
	v_mfma_f32_16x16x32_bf16 v[26:29], v[150:153], v[188:191], v[26:29]
	v_mfma_f32_16x16x32_bf16 v[18:21], v[142:145], v[196:199], v[18:21]
	v_mfma_f32_16x16x32_bf16 v[10:13], v[150:153], v[196:199], v[10:13]
.La3_skip7:
	s_setprio 0
	s_barrier
	s_add_u32 s20, s20, 0x20080
	s_addc_u32 s21, s21, 0
	s_add_i32 s22, s22, s27
	v_lshl_add_u64 v[138:139], s[20:21], 0, v[0:1]
	s_mov_b32 m0, s22
	s_nop 0
	global_load_lds_dwordx4 v[138:139], off
	v_lshl_add_u64 v[138:139], s[20:21], 0, v[130:131]
	s_add_i32 m0, s22, 0x2000
	s_nop 0
	global_load_lds_dwordx4 v[138:139], off
	s_waitcnt vmcnt(6)
	s_barrier
	s_setprio 1
	s_cmp_lg_u32 s99, 0
	s_cbranch_scc1 .La3_skip8
	v_mfma_f32_16x16x32_bf16 v[54:57], v[230:233], v[154:157], v[54:57]
	v_mfma_f32_16x16x32_bf16 v[46:49], v[238:241], v[154:157], v[46:49]
	v_mfma_f32_16x16x32_bf16 v[38:41], v[230:233], v[176:179], v[38:41]
	v_mfma_f32_16x16x32_bf16 v[30:33], v[238:241], v[176:179], v[30:33]
	v_mfma_f32_16x16x32_bf16 v[22:25], v[230:233], v[184:187], v[22:25]
	v_mfma_f32_16x16x32_bf16 v[14:17], v[238:241], v[184:187], v[14:17]
	v_mfma_f32_16x16x32_bf16 v[6:9], v[230:233], v[192:195], v[6:9]
	v_mfma_f32_16x16x32_bf16 v[2:5], v[238:241], v[192:195], v[2:5]
	v_mfma_f32_16x16x32_bf16 v[54:57], v[234:237], v[158:161], v[54:57]
	v_mfma_f32_16x16x32_bf16 v[46:49], v[242:245], v[158:161], v[46:49]
	v_mfma_f32_16x16x32_bf16 v[38:41], v[234:237], v[180:183], v[38:41]
	v_mfma_f32_16x16x32_bf16 v[30:33], v[242:245], v[180:183], v[30:33]
	v_mfma_f32_16x16x32_bf16 v[22:25], v[234:237], v[188:191], v[22:25]
	v_mfma_f32_16x16x32_bf16 v[14:17], v[242:245], v[188:191], v[14:17]
	v_mfma_f32_16x16x32_bf16 v[6:9], v[234:237], v[196:199], v[6:9]
	v_mfma_f32_16x16x32_bf16 v[2:5], v[242:245], v[196:199], v[2:5]
.La3_skip8:
	s_setprio 0
	s_add_i32 s43, s43, 2
	s_add_u32 s41, s41, 0x100
	s_addc_u32 s42, s42, 0
	s_add_u32 s8, s8, 0x100
	s_addc_u32 s9, s9, 0
	s_cmp_gt_u32 s43, 1
	s_barrier
	s_cbranch_scc0 .LBB0_893
	v_mov_b32_e32 v138, v163
	s_lshl_b32 s7, s7, 8
	v_and_b32_e32 v139, 15, v138
	v_and_b32_e32 v140, 0xc0, v138
	v_ashrrev_i32_e32 v141, 2, v138
	v_lshrrev_b32_e32 v138, 1, v138
	v_and_b32_e32 v138, 24, v138
	v_or3_b32 v138, v140, s7, v138
	s_movk_i32 s7, 0xffc0
	v_and_or_b32 v139, v141, s7, v139
	v_lshl_add_u32 v140, s6, 8, v139
	v_readlane_b32 s98, v254, 0
	s_and_b32 s98, s98, s99
	s_lshl_b32 s98, s98, 7
	v_add_u32_e32 v140, s98, v140
	v_ashrrev_i32_e32 v141, 31, v140
	s_mov_b32 s20, 0x3db504f3
	s_movk_i32 s6, 0x1ff
	v_readlane_b32 s8, v254, 35
	v_lshlrev_b64 v[142:143], 11, v[140:141]
	v_pk_mul_f32 v[144:145], v[128:129], s[20:21] op_sel_hi:[1,0]
	v_pk_mul_f32 v[146:147], v[126:127], s[20:21] op_sel_hi:[1,0]
	v_pk_mul_f32 v[148:149], v[124:125], s[20:21] op_sel_hi:[1,0]
	v_pk_mul_f32 v[150:151], v[122:123], s[20:21] op_sel_hi:[1,0]
	v_cmp_lt_i32_e32 vcc, s6, v138
	v_readlane_b32 s9, v254, 36
	v_ashrrev_i32_e32 v139, 31, v138
	v_cndmask_b32_e32 v141, v129, v145, vcc
	v_cndmask_b32_e32 v144, v128, v144, vcc
	v_cndmask_b32_e32 v127, v127, v147, vcc
	v_cndmask_b32_e32 v126, v126, v146, vcc
	v_cndmask_b32_e32 v145, v125, v149, vcc
	v_cndmask_b32_e32 v146, v124, v148, vcc
	v_cndmask_b32_e32 v147, v123, v151, vcc
	v_cndmask_b32_e32 v148, v122, v150, vcc
	v_lshl_add_u64 v[122:123], s[8:9], 0, v[142:143]
	v_lshlrev_b64 v[128:129], 1, v[138:139]
	v_lshl_add_u64 v[122:123], v[122:123], 0, v[128:129]
	v_cvt_pk_bf16_f32 v124, v126, v127
	v_cvt_pk_bf16_f32 v125, v144, v141
	v_cvt_pk_bf16_f32 v126, v148, v147
	v_cvt_pk_bf16_f32 v127, v146, v145
	v_or_b32_e32 v141, 32, v138
	global_store_dwordx4 v[122:123], v[124:127], off
	v_pk_mul_f32 v[138:139], v[112:113], s[20:21] op_sel_hi:[1,0]
	v_pk_mul_f32 v[142:143], v[110:111], s[20:21] op_sel_hi:[1,0]
	v_pk_mul_f32 v[124:125], v[120:121], s[20:21] op_sel_hi:[1,0]
	v_pk_mul_f32 v[126:127], v[118:119], s[20:21] op_sel_hi:[1,0]
	v_cmp_lt_i32_e64 s[6:7], s6, v141
	s_nop 1
	v_cndmask_b32_e64 v121, v121, v125, s[6:7]
	v_cndmask_b32_e64 v120, v120, v124, s[6:7]
	v_cndmask_b32_e64 v119, v119, v127, s[6:7]
	v_cndmask_b32_e64 v118, v118, v126, s[6:7]
	v_cndmask_b32_e64 v113, v113, v139, s[6:7]
	v_cndmask_b32_e64 v124, v112, v138, s[6:7]
	v_cndmask_b32_e64 v112, v111, v143, s[6:7]
	v_cndmask_b32_e64 v125, v110, v142, s[6:7]
	v_cvt_pk_bf16_f32 v110, v118, v119
	v_cvt_pk_bf16_f32 v111, v120, v121
	v_cvt_pk_bf16_f32 v112, v125, v112
	v_cvt_pk_bf16_f32 v113, v124, v113
	global_store_dwordx4 v[122:123], v[110:113], off offset:64
	v_pk_mul_f32 v[118:119], v[114:115], s[20:21] op_sel_hi:[1,0]
	v_pk_mul_f32 v[120:121], v[108:109], s[20:21] op_sel_hi:[1,0]
	v_or_b32_e32 v110, 16, v140
	v_ashrrev_i32_e32 v111, 31, v110
	v_lshlrev_b64 v[110:111], 11, v[110:111]
	v_pk_mul_f32 v[112:113], v[116:117], s[20:21] op_sel_hi:[1,0]
	v_pk_mul_f32 v[124:125], v[106:107], s[20:21] op_sel_hi:[1,0]
	v_cndmask_b32_e32 v113, v117, v113, vcc
	v_cndmask_b32_e32 v112, v116, v112, vcc
	v_cndmask_b32_e32 v115, v115, v119, vcc
	v_cndmask_b32_e32 v114, v114, v118, vcc
	v_cndmask_b32_e32 v109, v109, v121, vcc
	v_cndmask_b32_e32 v116, v108, v120, vcc
	v_cndmask_b32_e32 v108, v107, v125, vcc
	v_cndmask_b32_e32 v117, v106, v124, vcc
	v_lshl_add_u64 v[106:107], s[8:9], 0, v[110:111]
	v_lshl_add_u64 v[110:111], v[106:107], 0, v[128:129]
	v_cvt_pk_bf16_f32 v106, v114, v115
	v_cvt_pk_bf16_f32 v107, v112, v113
	v_cvt_pk_bf16_f32 v108, v117, v108
	v_cvt_pk_bf16_f32 v109, v116, v109
	global_store_dwordx4 v[110:111], v[106:109], off
	v_pk_mul_f32 v[112:113], v[96:97], s[20:21] op_sel_hi:[1,0]
	v_pk_mul_f32 v[114:115], v[94:95], s[20:21] op_sel_hi:[1,0]
	v_pk_mul_f32 v[106:107], v[104:105], s[20:21] op_sel_hi:[1,0]
	v_pk_mul_f32 v[108:109], v[102:103], s[20:21] op_sel_hi:[1,0]
	v_cndmask_b32_e64 v105, v105, v107, s[6:7]
	v_cndmask_b32_e64 v104, v104, v106, s[6:7]
	v_cndmask_b32_e64 v103, v103, v109, s[6:7]
	v_cndmask_b32_e64 v102, v102, v108, s[6:7]
	v_cndmask_b32_e64 v97, v97, v113, s[6:7]
	v_cndmask_b32_e64 v106, v96, v112, s[6:7]
	v_cndmask_b32_e64 v96, v95, v115, s[6:7]
	v_cndmask_b32_e64 v107, v94, v114, s[6:7]
	v_cvt_pk_bf16_f32 v94, v102, v103
	v_cvt_pk_bf16_f32 v95, v104, v105
	v_cvt_pk_bf16_f32 v96, v107, v96
	v_cvt_pk_bf16_f32 v97, v106, v97
	global_store_dwordx4 v[110:111], v[94:97], off offset:64
	v_pk_mul_f32 v[102:103], v[98:99], s[20:21] op_sel_hi:[1,0]
	v_pk_mul_f32 v[104:105], v[92:93], s[20:21] op_sel_hi:[1,0]
	v_or_b32_e32 v94, 32, v140
	v_ashrrev_i32_e32 v95, 31, v94
	v_lshlrev_b64 v[94:95], 11, v[94:95]
	v_pk_mul_f32 v[96:97], v[100:101], s[20:21] op_sel_hi:[1,0]
	v_pk_mul_f32 v[106:107], v[90:91], s[20:21] op_sel_hi:[1,0]
	v_cndmask_b32_e32 v97, v101, v97, vcc
	v_cndmask_b32_e32 v96, v100, v96, vcc
	v_cndmask_b32_e32 v99, v99, v103, vcc
	v_cndmask_b32_e32 v98, v98, v102, vcc
	v_cndmask_b32_e32 v93, v93, v105, vcc
	v_cndmask_b32_e32 v100, v92, v104, vcc
	v_cndmask_b32_e32 v92, v91, v107, vcc
	v_cndmask_b32_e32 v101, v90, v106, vcc
	v_lshl_add_u64 v[90:91], s[8:9], 0, v[94:95]
	v_lshl_add_u64 v[94:95], v[90:91], 0, v[128:129]
	v_cvt_pk_bf16_f32 v90, v98, v99
	v_cvt_pk_bf16_f32 v91, v96, v97
	v_cvt_pk_bf16_f32 v92, v101, v92
	v_cvt_pk_bf16_f32 v93, v100, v93
	global_store_dwordx4 v[94:95], v[90:93], off
	v_pk_mul_f32 v[96:97], v[80:81], s[20:21] op_sel_hi:[1,0]
	v_pk_mul_f32 v[98:99], v[78:79], s[20:21] op_sel_hi:[1,0]
	v_pk_mul_f32 v[90:91], v[88:89], s[20:21] op_sel_hi:[1,0]
	v_pk_mul_f32 v[92:93], v[86:87], s[20:21] op_sel_hi:[1,0]
	v_cndmask_b32_e64 v89, v89, v91, s[6:7]
	v_cndmask_b32_e64 v88, v88, v90, s[6:7]
	v_cndmask_b32_e64 v87, v87, v93, s[6:7]
	v_cndmask_b32_e64 v86, v86, v92, s[6:7]
	v_cndmask_b32_e64 v81, v81, v97, s[6:7]
	v_cndmask_b32_e64 v90, v80, v96, s[6:7]
	v_cndmask_b32_e64 v80, v79, v99, s[6:7]
	v_cndmask_b32_e64 v91, v78, v98, s[6:7]
	v_cvt_pk_bf16_f32 v78, v86, v87
	v_cvt_pk_bf16_f32 v79, v88, v89
	v_cvt_pk_bf16_f32 v80, v91, v80
	v_cvt_pk_bf16_f32 v81, v90, v81
	global_store_dwordx4 v[94:95], v[78:81], off offset:64
	v_pk_mul_f32 v[86:87], v[82:83], s[20:21] op_sel_hi:[1,0]
	v_pk_mul_f32 v[88:89], v[76:77], s[20:21] op_sel_hi:[1,0]
	v_or_b32_e32 v78, 48, v140
	v_ashrrev_i32_e32 v79, 31, v78
	v_lshlrev_b64 v[78:79], 11, v[78:79]
	v_pk_mul_f32 v[80:81], v[84:85], s[20:21] op_sel_hi:[1,0]
	v_pk_mul_f32 v[90:91], v[74:75], s[20:21] op_sel_hi:[1,0]
	v_cndmask_b32_e32 v81, v85, v81, vcc
	v_cndmask_b32_e32 v80, v84, v80, vcc
	v_cndmask_b32_e32 v83, v83, v87, vcc
	v_cndmask_b32_e32 v82, v82, v86, vcc
	v_cndmask_b32_e32 v77, v77, v89, vcc
	v_cndmask_b32_e32 v84, v76, v88, vcc
	v_cndmask_b32_e32 v76, v75, v91, vcc
	v_cndmask_b32_e32 v85, v74, v90, vcc
	v_lshl_add_u64 v[74:75], s[8:9], 0, v[78:79]
	v_lshl_add_u64 v[78:79], v[74:75], 0, v[128:129]
	v_cvt_pk_bf16_f32 v74, v82, v83
	v_cvt_pk_bf16_f32 v75, v80, v81
	v_cvt_pk_bf16_f32 v76, v85, v76
	v_cvt_pk_bf16_f32 v77, v84, v77
	global_store_dwordx4 v[78:79], v[74:77], off
	v_pk_mul_f32 v[80:81], v[68:69], s[20:21] op_sel_hi:[1,0]
	v_pk_mul_f32 v[82:83], v[66:67], s[20:21] op_sel_hi:[1,0]
	v_pk_mul_f32 v[74:75], v[72:73], s[20:21] op_sel_hi:[1,0]
	v_pk_mul_f32 v[76:77], v[70:71], s[20:21] op_sel_hi:[1,0]
	v_cndmask_b32_e64 v73, v73, v75, s[6:7]
	v_cndmask_b32_e64 v72, v72, v74, s[6:7]
	v_cndmask_b32_e64 v71, v71, v77, s[6:7]
	v_cndmask_b32_e64 v70, v70, v76, s[6:7]
	v_cndmask_b32_e64 v69, v69, v81, s[6:7]
	v_cndmask_b32_e64 v74, v68, v80, s[6:7]
	v_cndmask_b32_e64 v68, v67, v83, s[6:7]
	v_cndmask_b32_e64 v75, v66, v82, s[6:7]
	v_cvt_pk_bf16_f32 v66, v70, v71
	v_cvt_pk_bf16_f32 v67, v72, v73
	v_cvt_pk_bf16_f32 v68, v75, v68
	v_cvt_pk_bf16_f32 v69, v74, v69
	global_store_dwordx4 v[78:79], v[66:69], off offset:64
	s_cmp_lg_u32 s99, 0
	s_cbranch_scc1 .La3_half_done
	s_mov_b64 s[8:9], 0x40000
	v_pk_mul_f32 v[70:71], v[60:61], s[20:21] op_sel_hi:[1,0]
	v_pk_mul_f32 v[66:67], v[64:65], s[20:21] op_sel_hi:[1,0]
	v_pk_mul_f32 v[68:69], v[62:63], s[20:21] op_sel_hi:[1,0]
	v_pk_mul_f32 v[72:73], v[58:59], s[20:21] op_sel_hi:[1,0]
	v_cndmask_b32_e32 v65, v65, v67, vcc
	v_cndmask_b32_e32 v64, v64, v66, vcc
	v_cndmask_b32_e32 v66, v63, v69, vcc
	v_cndmask_b32_e32 v67, v62, v68, vcc
	v_lshl_add_u64 v[62:63], v[122:123], 0, s[8:9]
	s_mov_b32 s8, 0x40000
	v_cndmask_b32_e32 v61, v61, v71, vcc
	v_cndmask_b32_e32 v68, v60, v70, vcc
	v_cndmask_b32_e32 v60, v59, v73, vcc
	v_cndmask_b32_e32 v69, v58, v72, vcc
	v_cvt_pk_bf16_f32 v59, v64, v65
	v_add_co_u32_e64 v64, s[8:9], s8, v122
	v_cvt_pk_bf16_f32 v58, v67, v66
	v_cvt_pk_bf16_f32 v60, v69, v60
	v_cvt_pk_bf16_f32 v61, v68, v61
	v_addc_co_u32_e64 v65, s[8:9], 0, v123, s[8:9]
	global_store_dwordx4 v[64:65], v[58:61], off
	v_pk_mul_f32 v[64:65], v[48:49], s[20:21] op_sel_hi:[1,0]
	v_pk_mul_f32 v[66:67], v[46:47], s[20:21] op_sel_hi:[1,0]
	v_pk_mul_f32 v[58:59], v[56:57], s[20:21] op_sel_hi:[1,0]
	v_pk_mul_f32 v[60:61], v[54:55], s[20:21] op_sel_hi:[1,0]
	v_cndmask_b32_e64 v57, v57, v59, s[6:7]
	v_cndmask_b32_e64 v56, v56, v58, s[6:7]
	v_cndmask_b32_e64 v55, v55, v61, s[6:7]
	v_cndmask_b32_e64 v54, v54, v60, s[6:7]
	v_cndmask_b32_e64 v49, v49, v65, s[6:7]
	v_cndmask_b32_e64 v58, v48, v64, s[6:7]
	v_cndmask_b32_e64 v48, v47, v67, s[6:7]
	v_cndmask_b32_e64 v59, v46, v66, s[6:7]
	v_cvt_pk_bf16_f32 v46, v54, v55
	v_cvt_pk_bf16_f32 v47, v56, v57
	v_cvt_pk_bf16_f32 v48, v59, v48
	v_cvt_pk_bf16_f32 v49, v58, v49
	global_store_dwordx4 v[62:63], v[46:49], off offset:64
	v_pk_mul_f32 v[54:55], v[44:45], s[20:21] op_sel_hi:[1,0]
	v_pk_mul_f32 v[56:57], v[42:43], s[20:21] op_sel_hi:[1,0]
	v_pk_mul_f32 v[48:49], v[50:51], s[20:21] op_sel_hi:[1,0]
	v_pk_mul_f32 v[46:47], v[52:53], s[20:21] op_sel_hi:[1,0]
	v_cndmask_b32_e32 v49, v51, v49, vcc
	v_cndmask_b32_e32 v48, v50, v48, vcc
	s_mov_b64 s[8:9], 0x48000
	v_cndmask_b32_e32 v53, v53, v47, vcc
	v_cndmask_b32_e32 v52, v52, v46, vcc
	v_cndmask_b32_e32 v45, v45, v55, vcc
	v_cndmask_b32_e32 v50, v44, v54, vcc
	v_cndmask_b32_e32 v44, v43, v57, vcc
	v_cndmask_b32_e32 v51, v42, v56, vcc
	v_lshl_add_u64 v[46:47], v[122:123], 0, s[8:9]
	v_cvt_pk_bf16_f32 v42, v48, v49
	v_add_co_u32_e64 v48, s[8:9], s95, v122
	v_cvt_pk_bf16_f32 v43, v52, v53
	v_cvt_pk_bf16_f32 v44, v51, v44
	v_cvt_pk_bf16_f32 v45, v50, v45
	v_addc_co_u32_e64 v49, s[8:9], 0, v123, s[8:9]
	global_store_dwordx4 v[48:49], v[42:45], off
	v_pk_mul_f32 v[48:49], v[32:33], s[20:21] op_sel_hi:[1,0]
	v_pk_mul_f32 v[50:51], v[30:31], s[20:21] op_sel_hi:[1,0]
	v_pk_mul_f32 v[42:43], v[40:41], s[20:21] op_sel_hi:[1,0]
	v_pk_mul_f32 v[44:45], v[38:39], s[20:21] op_sel_hi:[1,0]
	v_cndmask_b32_e64 v41, v41, v43, s[6:7]
	v_cndmask_b32_e64 v40, v40, v42, s[6:7]
	v_cndmask_b32_e64 v39, v39, v45, s[6:7]
	v_cndmask_b32_e64 v38, v38, v44, s[6:7]
	v_cndmask_b32_e64 v33, v33, v49, s[6:7]
	v_cndmask_b32_e64 v42, v32, v48, s[6:7]
	v_cndmask_b32_e64 v32, v31, v51, s[6:7]
	v_cndmask_b32_e64 v43, v30, v50, s[6:7]
	v_cvt_pk_bf16_f32 v30, v38, v39
	v_cvt_pk_bf16_f32 v31, v40, v41
	v_cvt_pk_bf16_f32 v32, v43, v32
	v_cvt_pk_bf16_f32 v33, v42, v33
	global_store_dwordx4 v[46:47], v[30:33], off offset:64
	s_mov_b64 s[8:9], 0x50000
	v_pk_mul_f32 v[38:39], v[28:29], s[20:21] op_sel_hi:[1,0]
	v_pk_mul_f32 v[30:31], v[36:37], s[20:21] op_sel_hi:[1,0]
	v_pk_mul_f32 v[32:33], v[34:35], s[20:21] op_sel_hi:[1,0]
	v_pk_mul_f32 v[40:41], v[26:27], s[20:21] op_sel_hi:[1,0]
	v_cndmask_b32_e32 v37, v37, v31, vcc
	v_cndmask_b32_e32 v36, v36, v30, vcc
	v_cndmask_b32_e32 v33, v35, v33, vcc
	v_cndmask_b32_e32 v32, v34, v32, vcc
	v_lshl_add_u64 v[30:31], v[122:123], 0, s[8:9]
	s_mov_b32 s8, 0x50000
	v_cndmask_b32_e32 v29, v29, v39, vcc
	v_cndmask_b32_e32 v34, v28, v38, vcc
	v_cndmask_b32_e32 v28, v27, v41, vcc
	v_cndmask_b32_e32 v35, v26, v40, vcc
	v_cvt_pk_bf16_f32 v26, v32, v33
	v_add_co_u32_e64 v32, s[8:9], s8, v122
	v_cvt_pk_bf16_f32 v27, v36, v37
	v_cvt_pk_bf16_f32 v28, v35, v28
	v_cvt_pk_bf16_f32 v29, v34, v29
	v_addc_co_u32_e64 v33, s[8:9], 0, v123, s[8:9]
	global_store_dwordx4 v[32:33], v[26:29], off
	v_pk_mul_f32 v[32:33], v[16:17], s[20:21] op_sel_hi:[1,0]
	v_pk_mul_f32 v[34:35], v[14:15], s[20:21] op_sel_hi:[1,0]
	v_pk_mul_f32 v[26:27], v[24:25], s[20:21] op_sel_hi:[1,0]
	v_pk_mul_f32 v[28:29], v[22:23], s[20:21] op_sel_hi:[1,0]
	v_cndmask_b32_e64 v25, v25, v27, s[6:7]
	v_cndmask_b32_e64 v24, v24, v26, s[6:7]
	v_cndmask_b32_e64 v23, v23, v29, s[6:7]
	v_cndmask_b32_e64 v22, v22, v28, s[6:7]
	v_cndmask_b32_e64 v17, v17, v33, s[6:7]
	v_cndmask_b32_e64 v26, v16, v32, s[6:7]
	v_cndmask_b32_e64 v16, v15, v35, s[6:7]
	v_cndmask_b32_e64 v27, v14, v34, s[6:7]
	v_cvt_pk_bf16_f32 v14, v22, v23
	v_cvt_pk_bf16_f32 v15, v24, v25
	v_cvt_pk_bf16_f32 v16, v27, v16
	v_cvt_pk_bf16_f32 v17, v26, v17
	global_store_dwordx4 v[30:31], v[14:17], off offset:64
	s_mov_b64 s[8:9], 0x58000
	v_pk_mul_f32 v[22:23], v[12:13], s[20:21] op_sel_hi:[1,0]
	v_pk_mul_f32 v[14:15], v[20:21], s[20:21] op_sel_hi:[1,0]
	v_pk_mul_f32 v[16:17], v[18:19], s[20:21] op_sel_hi:[1,0]
	v_pk_mul_f32 v[24:25], v[10:11], s[20:21] op_sel_hi:[1,0]
	v_cndmask_b32_e32 v21, v21, v15, vcc
	v_cndmask_b32_e32 v20, v20, v14, vcc
	v_cndmask_b32_e32 v17, v19, v17, vcc
	v_cndmask_b32_e32 v16, v18, v16, vcc
	v_lshl_add_u64 v[14:15], v[122:123], 0, s[8:9]
	s_mov_b32 s8, 0x58000
	v_cndmask_b32_e32 v13, v13, v23, vcc
	v_cndmask_b32_e32 v18, v12, v22, vcc
	v_cndmask_b32_e32 v12, v11, v25, vcc
	v_cndmask_b32_e32 v19, v10, v24, vcc
	v_cvt_pk_bf16_f32 v10, v16, v17
	v_add_co_u32_e32 v16, vcc, s8, v122
	v_cvt_pk_bf16_f32 v11, v20, v21
	v_cvt_pk_bf16_f32 v12, v19, v12
	v_cvt_pk_bf16_f32 v13, v18, v13
	v_addc_co_u32_e32 v17, vcc, 0, v123, vcc
	global_store_dwordx4 v[16:17], v[10:13], off
	v_pk_mul_f32 v[16:17], v[4:5], s[20:21] op_sel_hi:[1,0]
	v_pk_mul_f32 v[18:19], v[2:3], s[20:21] op_sel_hi:[1,0]
	v_pk_mul_f32 v[10:11], v[8:9], s[20:21] op_sel_hi:[1,0]
	v_pk_mul_f32 v[12:13], v[6:7], s[20:21] op_sel_hi:[1,0]
	v_cndmask_b32_e64 v9, v9, v11, s[6:7]
	v_cndmask_b32_e64 v8, v8, v10, s[6:7]
	v_cndmask_b32_e64 v7, v7, v13, s[6:7]
	v_cndmask_b32_e64 v6, v6, v12, s[6:7]
	v_cndmask_b32_e64 v5, v5, v17, s[6:7]
	v_cndmask_b32_e64 v10, v4, v16, s[6:7]
	v_cndmask_b32_e64 v4, v3, v19, s[6:7]
	v_cndmask_b32_e64 v11, v2, v18, s[6:7]
	v_cvt_pk_bf16_f32 v2, v6, v7
	v_cvt_pk_bf16_f32 v3, v8, v9
	v_cvt_pk_bf16_f32 v4, v11, v4
	v_cvt_pk_bf16_f32 v5, v10, v5
	s_and_b64 vcc, exec, s[4:5]
	s_mov_b32 s7, s10
	s_mov_b32 s6, s12
	s_mov_b64 s[8:9], s[18:19]
	s_mov_b64 s[20:21], s[16:17]
	global_store_dwordx4 v[14:15], v[2:5], off offset:64
	s_cbranch_vccz .LBB0_890
	s_branch .La3_exit
.La3_half_done:
	s_and_b64 vcc, exec, s[4:5]
	s_mov_b32 s7, s10
	s_mov_b32 s6, s12
	s_mov_b64 s[8:9], s[18:19]
	s_mov_b64 s[20:21], s[16:17]
	s_cbranch_vccz .LBB0_890
